# compressed-branch loops: constant-bias unmasked path for blocks that lie entirely beyond the bias table (no per-key table reads, no masks)
# speedup vs baseline: 1.0099x; 1.0060x over previous
; #define LAS __attribute__((address_space(3)))
; template <int MODE>
; __device__ __forceinline__ void softmax_block(f32x4 (&acc)[4], int base, bool ok, int t, int g4, const LAS float* lutg, SmState& st, f32x4 (&O)[4], bf16x8 (&pB)[2]) {
;     float mx = -1e30f; unsigned vm = 0u;
; #pragma unroll
;     for (int nt = 0; nt < 4; ++nt)
; #pragma unroll
;         for (int i = 0; i < 4; ++i) {
;             const int key = base + 16 * nt + 4 * g4 + i;
;             const int dist = (MODE == 0) ? t - (16 * key + 31) : t - key;
;             bool valid = dist >= 0;
;             if (MODE == 1) valid = valid && ok;
;             if (MODE == 2) valid = valid && dist < 512;
;             int dc = dist < 0 ? 0 : dist; dc = dc > 1023 ? 1023 : dc;
;             const float lg = acc[nt][i] + lutg[dc * 4];
; __device__ __forceinline__ void nsa_wave(CArgs* Ap, int l, int b, int g, int tq0, const LAS float* lut, LAS float* imp, int lane) {
;     ...
;         for (int cb = 0; cb < ncb; ++cb) {
;             bf16x8 kf[4][2]; load_k(kf, KC + (size_t)cb * 4096, lane);
;             f32x4 acc[4];
; #pragma unroll
;             for (int nt = 0; nt < 4; ++nt) acc[nt] = (f32x4){0.f, 0.f, 0.f, 0.f};
;             qk_acc(acc, kf, qB);
;             softmax_block<0>(acc, cb * 64, true, t, g4, lutg, st, Od, pB);
.LBB0_895:
	s_lshl_b32 s20, s0, 2
	s_sub_i32 s0, s19, 28
	s_lshr_b32 s21, s0, 10
	v_lshl_add_u32 v206, s17, 14, v132
	s_andn2_b64 vcc, exec, s[46:47]
	v_add_u32_e32 v75, s18, v202
	s_cbranch_vccnz .LBB0_899
	s_add_i32 s0, s20, s17
	s_ashr_i32 s1, s0, 31
	s_add_i32 s72, s21, 1
	s_lshl_b64 s[0:1], s[0:1], 16
	s_add_u32 s0, s15, s0
	s_addc_u32 s1, s16, s1
	v_xor_b32_e32 v21, 16, v170
	v_xor_b32_e32 v22, 32, v170
	v_lshl_add_u64 v[102:103], s[0:1], 0, v[84:85]
	s_mov_b32 s23, 0x2a201000
	v_add_co_u32_e32 v100, vcc, s23, v102
	v_add_u32_e32 v122, s18, v202
	s_mov_b64 s[0:1], 0x2000
	v_addc_co_u32_e32 v101, vcc, 0, v103, vcc
	v_mov_b32_e32 v76, 0xf149f2ca
	v_mov_b32_e32 v8, 0
	global_load_dwordx4 v[24:27], v[100:101], off offset:-4096
	global_load_dwordx4 v[28:31], v[100:101], off offset:-3072
	global_load_dwordx4 v[32:35], v[100:101], off offset:-2048
	global_load_dwordx4 v[36:39], v[100:101], off offset:-1024
	global_load_dwordx4 v[40:43], v[100:101], off offset:0
	global_load_dwordx4 v[44:47], v[100:101], off offset:1024
	global_load_dwordx4 v[48:51], v[100:101], off offset:2048
	global_load_dwordx4 v[52:55], v[100:101], off offset:3072
	ds_read_b32 v125, v206 offset:16368
.Lc1_loop:
	v_cmp_lt_i32_e32 vcc, 0x3fe, v122
	s_cmp_eq_u64 vcc, exec
	s_cselect_b32 s26, 1, 0
	s_cbranch_scc1 .Lc1_lutskip
	v_add_u32_e32 v244, 0x330, v122
	v_cmp_lt_i32_e64 s[46:47], -1, v244
	v_med3_i32 v244, v244, 0, v181
	v_lshl_add_u32 v244, v244, 4, v206
	ds_read_b32 v244, v244
	v_add_u32_e32 v245, 0x320, v122
	v_cmp_lt_i32_e64 s[48:49], -1, v245
	v_med3_i32 v245, v245, 0, v181
	v_lshl_add_u32 v245, v245, 4, v206
	ds_read_b32 v245, v245
	v_add_u32_e32 v246, 0x310, v122
	v_cmp_lt_i32_e64 s[50:51], -1, v246
	v_med3_i32 v246, v246, 0, v181
	v_lshl_add_u32 v246, v246, 4, v206
	ds_read_b32 v246, v246
	v_add_u32_e32 v247, 0x300, v122
	v_cmp_lt_i32_e64 s[52:53], -1, v247
	v_med3_i32 v247, v247, 0, v181
	v_lshl_add_u32 v247, v247, 4, v206
	ds_read_b32 v247, v247
	v_add_u32_e32 v248, 0x230, v122
	v_cmp_lt_i32_e64 s[54:55], -1, v248
	v_med3_i32 v248, v248, 0, v181
	v_lshl_add_u32 v248, v248, 4, v206
	ds_read_b32 v248, v248
	v_add_u32_e32 v249, 0x220, v122
	v_cmp_lt_i32_e64 s[56:57], -1, v249
	v_med3_i32 v249, v249, 0, v181
	v_lshl_add_u32 v249, v249, 4, v206
	ds_read_b32 v249, v249
	v_add_u32_e32 v250, 0x210, v122
	v_cmp_lt_i32_e64 s[58:59], -1, v250
	v_med3_i32 v250, v250, 0, v181
	v_lshl_add_u32 v250, v250, 4, v206
	ds_read_b32 v250, v250
	v_add_u32_e32 v251, 0x200, v122
	v_cmp_lt_i32_e64 s[60:61], -1, v251
	v_med3_i32 v251, v251, 0, v181
	v_lshl_add_u32 v251, v251, 4, v206
	ds_read_b32 v251, v251
	v_add_u32_e32 v252, 0x130, v122
	v_cmp_lt_i32_e64 s[62:63], -1, v252
	v_med3_i32 v252, v252, 0, v181
	v_lshl_add_u32 v252, v252, 4, v206
	ds_read_b32 v252, v252
	v_add_u32_e32 v253, 0x120, v122
	v_cmp_lt_i32_e64 s[64:65], -1, v253
	v_med3_i32 v253, v253, 0, v181
	v_lshl_add_u32 v253, v253, 4, v206
	ds_read_b32 v253, v253
	v_add_u32_e32 v255, 0x110, v122
	v_cmp_lt_i32_e64 s[66:67], -1, v255
	v_med3_i32 v255, v255, 0, v181
	v_lshl_add_u32 v255, v255, 4, v206
	ds_read_b32 v255, v255
	v_add_u32_e32 v98, 0x100, v122
	v_cmp_lt_i32_e64 s[68:69], -1, v98
	v_med3_i32 v98, v98, 0, v181
	v_lshl_add_u32 v98, v98, 4, v206
	ds_read_b32 v98, v98
	v_add_u32_e32 v99, 0x30, v122
	v_cmp_lt_i32_e64 s[24:25], -1, v99
	v_med3_i32 v99, v99, 0, v181
	v_lshl_add_u32 v99, v99, 4, v206
	ds_read_b32 v99, v99
	v_add_u32_e32 v116, 0x20, v122
	v_cmp_lt_i32_e64 s[98:99], -1, v116
	v_med3_i32 v116, v116, 0, v181
	v_lshl_add_u32 v116, v116, 4, v206
	ds_read_b32 v116, v116
	v_add_u32_e32 v117, 0x10, v122
	v_cmp_lt_i32_e64 s[100:101], -1, v117
	v_med3_i32 v117, v117, 0, v181
	v_lshl_add_u32 v117, v117, 4, v206
	ds_read_b32 v117, v117
	v_add_u32_e32 v118, 0x0, v122
	v_cmp_lt_i32_e64 s[22:23], -1, v118
	v_med3_i32 v118, v118, 0, v181
	v_lshl_add_u32 v118, v118, 4, v206
	ds_read_b32 v118, v118
.Lc1_lutskip:
	v_add_u32_e32 v122, 0xfffffc00, v122
	s_add_i32 s72, s72, -1
	s_waitcnt vmcnt(0)
	v_mfma_f32_16x16x32_bf16 v[228:231], v[24:27], v[0:3], 0
	v_mfma_f32_16x16x32_bf16 v[232:235], v[32:35], v[0:3], 0
	v_mfma_f32_16x16x32_bf16 v[236:239], v[40:43], v[0:3], 0
	v_mfma_f32_16x16x32_bf16 v[240:243], v[48:51], v[0:3], 0
	v_mfma_f32_16x16x32_bf16 v[228:231], v[28:31], v[4:7], v[228:231]
	v_mfma_f32_16x16x32_bf16 v[232:235], v[36:39], v[4:7], v[232:235]
	v_mfma_f32_16x16x32_bf16 v[236:239], v[44:47], v[4:7], v[236:239]
	v_mfma_f32_16x16x32_bf16 v[240:243], v[52:55], v[4:7], v[240:243]
	s_cmp_eq_u32 s72, 0
	s_cbranch_scc1 .Lc1_nokpf
	v_lshl_add_u64 v[100:101], v[100:101], 0, s[0:1]
	global_load_dwordx4 v[24:27], v[100:101], off offset:-4096
	global_load_dwordx4 v[28:31], v[100:101], off offset:-3072
	global_load_dwordx4 v[32:35], v[100:101], off offset:-2048
	global_load_dwordx4 v[36:39], v[100:101], off offset:-1024
	global_load_dwordx4 v[40:43], v[100:101], off offset:0
	global_load_dwordx4 v[44:47], v[100:101], off offset:1024
	global_load_dwordx4 v[48:51], v[100:101], off offset:2048
	global_load_dwordx4 v[52:55], v[100:101], off offset:3072
; #define LAS __attribute__((address_space(3)))
; __device__ __forceinline__ float fexp(float x) { return __expf(x); }
; template <int MODE>
; __device__ __forceinline__ void softmax_block(f32x4 (&acc)[4], int base, bool ok, int t, int g4, const LAS float* lutg, SmState& st, f32x4 (&O)[4], bf16x8 (&pB)[2]) {
;     float mx = -1e30f; unsigned vm = 0u;
; #pragma unroll
;     for (int nt = 0; nt < 4; ++nt)
; #pragma unroll
;         for (int i = 0; i < 4; ++i) {
;             const int key = base + 16 * nt + 4 * g4 + i;
;             const int dist = (MODE == 0) ? t - (16 * key + 31) : t - key;
;             bool valid = dist >= 0;
;             if (MODE == 1) valid = valid && ok;
;             if (MODE == 2) valid = valid && dist < 512;
;             int dc = dist < 0 ? 0 : dist; dc = dc > 1023 ? 1023 : dc;
;             const float lg = acc[nt][i] + lutg[dc * 4];
;             acc[nt][i] = lg;
;             if (valid) { mx = fmaxf(mx, lg); vm |= 1u << (nt * 4 + i); }
;         }
;     mx = fmaxf(mx, __shfl_xor(mx, 16)); mx = fmaxf(mx, __shfl_xor(mx, 32));
;     const float mn = fmaxf(st.m, mx);
;     const float sc = fexp(st.m - mn);
;     float ls = 0.f;
; #pragma unroll
;     for (int nt = 0; nt < 4; ++nt)
; #pragma unroll
;         for (int i = 0; i < 4; ++i) { const float p = ((vm >> (nt * 4 + i)) & 1u) ? fexp(acc[nt][i] - mn) : 0.f; acc[nt][i] = p; ls += p; }
;     st.l = st.l * sc + ls; st.m = mn;
.Lc1_nokpf:
	s_waitcnt lgkmcnt(0)
	s_nop 7
	s_cmp_lg_u32 s26, 0
	s_cbranch_scc0 .Lc1_gen
	v_add_f32_e32 v228, v228, v125
	v_add_f32_e32 v229, v229, v125
	v_add_f32_e32 v230, v230, v125
	v_add_f32_e32 v231, v231, v125
	v_add_f32_e32 v232, v232, v125
	v_add_f32_e32 v233, v233, v125
	v_add_f32_e32 v234, v234, v125
	v_add_f32_e32 v235, v235, v125
	v_add_f32_e32 v236, v236, v125
	v_add_f32_e32 v237, v237, v125
	v_add_f32_e32 v238, v238, v125
	v_add_f32_e32 v239, v239, v125
	v_add_f32_e32 v240, v240, v125
	v_add_f32_e32 v241, v241, v125
	v_add_f32_e32 v242, v242, v125
	v_add_f32_e32 v243, v243, v125
	v_max3_f32 v244, v228, v229, v230
	v_max3_f32 v247, v231, v232, v233
	v_max3_f32 v250, v234, v235, v236
	v_max3_f32 v253, v237, v238, v239
	v_max3_f32 v99, v240, v241, v242
	v_max3_f32 v244, v244, v247, v250
	v_max3_f32 v253, v253, v99, v243
	v_max_f32_e32 v244, v244, v253
	v_mov_b32_e32 v120, v244
	s_nop 1
	v_permlane16_swap_b32_e32 v244, v120
	v_max_f32_e32 v244, v244, v120
	v_mov_b32_e32 v120, v244
	s_nop 1
	v_permlane32_swap_b32_e32 v244, v120
	v_max3_f32 v124, v76, v244, v120
	v_sub_f32_e32 v126, v76, v124
	v_mul_f32_e32 v120, 0xbfb8aa3b, v124
	v_mul_f32_e32 v126, 0x3fb8aa3b, v126
	v_fmamk_f32 v228, v228, 0x3fb8aa3b, v120
	v_fmamk_f32 v229, v229, 0x3fb8aa3b, v120
	v_fmamk_f32 v230, v230, 0x3fb8aa3b, v120
	v_fmamk_f32 v231, v231, 0x3fb8aa3b, v120
	v_fmamk_f32 v232, v232, 0x3fb8aa3b, v120
	v_fmamk_f32 v233, v233, 0x3fb8aa3b, v120
	v_fmamk_f32 v234, v234, 0x3fb8aa3b, v120
	v_fmamk_f32 v235, v235, 0x3fb8aa3b, v120
	v_fmamk_f32 v236, v236, 0x3fb8aa3b, v120
	v_fmamk_f32 v237, v237, 0x3fb8aa3b, v120
	v_fmamk_f32 v238, v238, 0x3fb8aa3b, v120
	v_fmamk_f32 v239, v239, 0x3fb8aa3b, v120
	v_fmamk_f32 v240, v240, 0x3fb8aa3b, v120
	v_fmamk_f32 v241, v241, 0x3fb8aa3b, v120
	v_fmamk_f32 v242, v242, 0x3fb8aa3b, v120
	v_fmamk_f32 v243, v243, 0x3fb8aa3b, v120
	v_exp_f32_e32 v126, v126
	v_exp_f32_e32 v228, v228
	v_exp_f32_e32 v229, v229
	v_exp_f32_e32 v230, v230
	v_exp_f32_e32 v231, v231
	v_exp_f32_e32 v232, v232
	v_exp_f32_e32 v233, v233
	v_exp_f32_e32 v234, v234
	v_exp_f32_e32 v235, v235
	v_exp_f32_e32 v236, v236
	v_exp_f32_e32 v237, v237
	v_exp_f32_e32 v238, v238
	v_exp_f32_e32 v239, v239
	v_exp_f32_e32 v240, v240
	v_exp_f32_e32 v241, v241
	v_exp_f32_e32 v242, v242
	v_exp_f32_e32 v243, v243
	v_mov_b32_e32 v76, v124
	s_branch .Lc1_join
.Lc1_gen:
	v_add_f32_e32 v228, v228, v244
	v_add_f32_e32 v229, v229, v245
	v_add_f32_e32 v230, v230, v246
	v_add_f32_e32 v231, v231, v247
	v_add_f32_e32 v232, v232, v248
	v_add_f32_e32 v233, v233, v249
	v_add_f32_e32 v234, v234, v250
	v_add_f32_e32 v235, v235, v251
	v_add_f32_e32 v236, v236, v252
	v_add_f32_e32 v237, v237, v253
	v_add_f32_e32 v238, v238, v255
	v_add_f32_e32 v239, v239, v98
	v_add_f32_e32 v240, v240, v99
	v_add_f32_e32 v241, v241, v116
	v_add_f32_e32 v242, v242, v117
	v_add_f32_e32 v243, v243, v118
	v_cndmask_b32_e64 v244, v182, v228, s[46:47]
	v_cndmask_b32_e64 v245, v182, v229, s[48:49]
	v_cndmask_b32_e64 v246, v182, v230, s[50:51]
	v_cndmask_b32_e64 v247, v182, v231, s[52:53]
	v_cndmask_b32_e64 v248, v182, v232, s[54:55]
	v_cndmask_b32_e64 v249, v182, v233, s[56:57]
	v_cndmask_b32_e64 v250, v182, v234, s[58:59]
	v_cndmask_b32_e64 v251, v182, v235, s[60:61]
	v_cndmask_b32_e64 v252, v182, v236, s[62:63]
	v_cndmask_b32_e64 v253, v182, v237, s[64:65]
	v_cndmask_b32_e64 v255, v182, v238, s[66:67]
	v_cndmask_b32_e64 v98, v182, v239, s[68:69]
	v_cndmask_b32_e64 v99, v182, v240, s[24:25]
	v_cndmask_b32_e64 v116, v182, v241, s[98:99]
	v_cndmask_b32_e64 v117, v182, v242, s[100:101]
	v_cndmask_b32_e64 v118, v182, v243, s[22:23]
	v_max3_f32 v244, v244, v245, v246
	v_max3_f32 v247, v247, v248, v249
	v_max3_f32 v250, v250, v251, v252
	v_max3_f32 v253, v253, v255, v98
	v_max3_f32 v99, v99, v116, v117
	v_max3_f32 v244, v244, v247, v250
	v_max3_f32 v253, v253, v99, v118
	v_max_f32_e32 v244, v244, v253
	v_mov_b32_e32 v120, v244
	s_nop 1
	v_permlane16_swap_b32_e32 v244, v120
	v_max_f32_e32 v244, v244, v120
	v_mov_b32_e32 v120, v244
	s_nop 1
	v_permlane32_swap_b32_e32 v244, v120
	v_max3_f32 v124, v76, v244, v120
	v_sub_f32_e32 v126, v76, v124
	v_mul_f32_e32 v120, 0xbfb8aa3b, v124
	v_mul_f32_e32 v126, 0x3fb8aa3b, v126
	v_fmamk_f32 v228, v228, 0x3fb8aa3b, v120
	v_fmamk_f32 v229, v229, 0x3fb8aa3b, v120
	v_fmamk_f32 v230, v230, 0x3fb8aa3b, v120
	v_fmamk_f32 v231, v231, 0x3fb8aa3b, v120
	v_fmamk_f32 v232, v232, 0x3fb8aa3b, v120
	v_fmamk_f32 v233, v233, 0x3fb8aa3b, v120
	v_fmamk_f32 v234, v234, 0x3fb8aa3b, v120
	v_fmamk_f32 v235, v235, 0x3fb8aa3b, v120
	v_fmamk_f32 v236, v236, 0x3fb8aa3b, v120
	v_fmamk_f32 v237, v237, 0x3fb8aa3b, v120
	v_fmamk_f32 v238, v238, 0x3fb8aa3b, v120
	v_fmamk_f32 v239, v239, 0x3fb8aa3b, v120
	v_fmamk_f32 v240, v240, 0x3fb8aa3b, v120
	v_fmamk_f32 v241, v241, 0x3fb8aa3b, v120
	v_fmamk_f32 v242, v242, 0x3fb8aa3b, v120
	v_fmamk_f32 v243, v243, 0x3fb8aa3b, v120
	v_exp_f32_e32 v126, v126
	v_exp_f32_e32 v228, v228
	v_exp_f32_e32 v229, v229
	v_exp_f32_e32 v230, v230
	v_exp_f32_e32 v231, v231
	v_exp_f32_e32 v232, v232
	v_exp_f32_e32 v233, v233
	v_exp_f32_e32 v234, v234
	v_exp_f32_e32 v235, v235
	v_exp_f32_e32 v236, v236
	v_exp_f32_e32 v237, v237
	v_exp_f32_e32 v238, v238
	v_exp_f32_e32 v239, v239
	v_exp_f32_e32 v240, v240
	v_exp_f32_e32 v241, v241
	v_exp_f32_e32 v242, v242
	v_exp_f32_e32 v243, v243
	v_mov_b32_e32 v76, v124
	v_cndmask_b32_e64 v228, 0, v228, s[46:47]
	v_cndmask_b32_e64 v229, 0, v229, s[48:49]
	v_cndmask_b32_e64 v230, 0, v230, s[50:51]
	v_cndmask_b32_e64 v231, 0, v231, s[52:53]
	v_cndmask_b32_e64 v232, 0, v232, s[54:55]
	v_cndmask_b32_e64 v233, 0, v233, s[56:57]
	v_cndmask_b32_e64 v234, 0, v234, s[58:59]
	v_cndmask_b32_e64 v235, 0, v235, s[60:61]
	v_cndmask_b32_e64 v236, 0, v236, s[62:63]
	v_cndmask_b32_e64 v237, 0, v237, s[64:65]
	v_cndmask_b32_e64 v238, 0, v238, s[66:67]
	v_cndmask_b32_e64 v239, 0, v239, s[68:69]
	v_cndmask_b32_e64 v240, 0, v240, s[24:25]
	v_cndmask_b32_e64 v241, 0, v241, s[98:99]
	v_cndmask_b32_e64 v242, 0, v242, s[100:101]
	v_cndmask_b32_e64 v243, 0, v243, s[22:23]
.Lc1_join:
	v_add_f32_e32 v120, v229, v228
	v_add_f32_e32 v120, v230, v120
	v_add_f32_e32 v120, v231, v120
	v_add_f32_e32 v120, v232, v120
	v_add_f32_e32 v120, v233, v120
	v_add_f32_e32 v120, v234, v120
	v_add_f32_e32 v120, v235, v120
	v_add_f32_e32 v120, v236, v120
	v_add_f32_e32 v120, v237, v120
	v_add_f32_e32 v120, v238, v120
	v_add_f32_e32 v120, v239, v120
	v_add_f32_e32 v120, v240, v120
	v_add_f32_e32 v120, v241, v120
	v_add_f32_e32 v120, v242, v120
	v_add_f32_e32 v120, v243, v120
	v_fmac_f32_e32 v120, v8, v126
	s_cmp_eq_u32 s72, 0
	v_mov_b32_e32 v8, v120
	s_cbranch_scc0 .Lc1_loop
	v_mov_b32_e32 v74, v170
	v_mov_b32_e32 v73, v177
	v_mov_b32_e32 v77, v171
	s_branch .LBB0_900

; __device__ __forceinline__ void nsa_wave(CArgs* Ap, int l, int b, int g, int tq0, const LAS float* lut, LAS float* imp, int lane) {
;     ...
;         for (int cb = 0; cb < ncb; ++cb) {
;             bf16x8 kf[4][2]; load_k(kf, KC + (size_t)cb * 4096, lane);
;             bf16x8 vf[4][2]; load_v(vf, VCT + (size_t)cb * 4096, lane);
;             f32x4 acc[4];
; #pragma unroll
;             for (int nt = 0; nt < 4; ++nt) acc[nt] = (f32x4){0.f, 0.f, 0.f, 0.f};
;             qk_acc(acc, kf, qB);
; #pragma unroll
;             for (int nt = 0; nt < 4; ++nt) {
;                 f32x4 pi4;
; #pragma unroll
;                 for (int i = 0; i < 4; ++i) {
;                     const int key = cb * 64 + 16 * nt + 4 * g4 + i; const int dist = t - (16 * key + 31);
;                     int dc = dist < 0 ? 0 : dist; dc = dc > 1023 ? 1023 : dc;
;                     const float lg = acc[nt][i] + lutg[dc * 4];
.Lc2_loop:
	v_cmp_lt_i32_e32 vcc, 0x3fe, v75
	s_cmp_eq_u64 vcc, exec
	s_cselect_b32 s26, 1, 0
	s_cbranch_scc1 .Lc2_lutskip
	v_add_u32_e32 v244, 0x330, v75
	v_cmp_lt_i32_e64 s[46:47], -1, v244
	v_min_u32_e32 v244, v181, v244
	v_lshl_add_u32 v244, v244, 4, v206
	ds_read_b32 v244, v244
	v_add_u32_e32 v245, 0x320, v75
	v_cmp_lt_i32_e64 s[48:49], -1, v245
	v_min_u32_e32 v245, v181, v245
	v_lshl_add_u32 v245, v245, 4, v206
	ds_read_b32 v245, v245
	v_add_u32_e32 v246, 0x310, v75
	v_cmp_lt_i32_e64 s[50:51], -1, v246
	v_min_u32_e32 v246, v181, v246
	v_lshl_add_u32 v246, v246, 4, v206
	ds_read_b32 v246, v246
	v_add_u32_e32 v247, 0x300, v75
	v_cmp_lt_i32_e64 s[52:53], -1, v247
	v_min_u32_e32 v247, v181, v247
	v_lshl_add_u32 v247, v247, 4, v206
	ds_read_b32 v247, v247
	v_add_u32_e32 v248, 0x230, v75
	v_cmp_lt_i32_e64 s[54:55], -1, v248
	v_min_u32_e32 v248, v181, v248
	v_lshl_add_u32 v248, v248, 4, v206
	ds_read_b32 v248, v248
	v_add_u32_e32 v249, 0x220, v75
	v_cmp_lt_i32_e64 s[56:57], -1, v249
	v_min_u32_e32 v249, v181, v249
	v_lshl_add_u32 v249, v249, 4, v206
	ds_read_b32 v249, v249
	v_add_u32_e32 v250, 0x210, v75
	v_cmp_lt_i32_e64 s[58:59], -1, v250
	v_min_u32_e32 v250, v181, v250
	v_lshl_add_u32 v250, v250, 4, v206
	ds_read_b32 v250, v250
	v_add_u32_e32 v251, 0x200, v75
	v_cmp_lt_i32_e64 s[60:61], -1, v251
	v_min_u32_e32 v251, v181, v251
	v_lshl_add_u32 v251, v251, 4, v206
	ds_read_b32 v251, v251
	v_add_u32_e32 v252, 0x130, v75
	v_cmp_lt_i32_e64 s[62:63], -1, v252
	v_min_u32_e32 v252, v181, v252
	v_lshl_add_u32 v252, v252, 4, v206
	ds_read_b32 v252, v252
	v_add_u32_e32 v253, 0x120, v75
	v_cmp_lt_i32_e64 s[64:65], -1, v253
	v_min_u32_e32 v253, v181, v253
	v_lshl_add_u32 v253, v253, 4, v206
	ds_read_b32 v253, v253
	v_add_u32_e32 v255, 0x110, v75
	v_cmp_lt_i32_e64 s[66:67], -1, v255
	v_min_u32_e32 v255, v181, v255
	v_lshl_add_u32 v255, v255, 4, v206
	ds_read_b32 v255, v255
	v_add_u32_e32 v98, 0x100, v75
	v_cmp_lt_i32_e64 s[68:69], -1, v98
	v_min_u32_e32 v98, v181, v98
	v_lshl_add_u32 v98, v98, 4, v206
	ds_read_b32 v98, v98
	v_add_u32_e32 v99, 0x30, v75
	v_cmp_lt_i32_e64 s[96:97], -1, v99
	v_min_u32_e32 v99, v181, v99
	v_lshl_add_u32 v99, v99, 4, v206
	ds_read_b32 v99, v99
	v_add_u32_e32 v116, 0x20, v75
	v_cmp_lt_i32_e64 s[98:99], -1, v116
	v_min_u32_e32 v116, v181, v116
	v_lshl_add_u32 v116, v116, 4, v206
	ds_read_b32 v116, v116
	v_add_u32_e32 v117, 0x10, v75
	v_cmp_lt_i32_e64 s[100:101], -1, v117
	v_min_u32_e32 v117, v181, v117
	v_lshl_add_u32 v117, v117, 4, v206
	ds_read_b32 v117, v117
	v_add_u32_e32 v118, 0x0, v75
	v_cmp_lt_i32_e64 s[76:77], -1, v118
	v_min_u32_e32 v118, v181, v118
	v_lshl_add_u32 v118, v118, 4, v206
	ds_read_b32 v118, v118
.Lc2_lutskip:
	v_add_u32_e32 v75, 0xfffffc00, v75
	s_addk_i32 s22, 0x100
	s_waitcnt vmcnt(8)
	v_mfma_f32_16x16x32_bf16 v[228:231], v[24:27], v[0:3], 0
	v_mfma_f32_16x16x32_bf16 v[232:235], v[32:35], v[0:3], 0
	v_mfma_f32_16x16x32_bf16 v[236:239], v[40:43], v[0:3], 0
	v_mfma_f32_16x16x32_bf16 v[240:243], v[48:51], v[0:3], 0
	v_mfma_f32_16x16x32_bf16 v[228:231], v[28:31], v[4:7], v[228:231]
	v_mfma_f32_16x16x32_bf16 v[232:235], v[36:39], v[4:7], v[232:235]
	v_mfma_f32_16x16x32_bf16 v[236:239], v[44:47], v[4:7], v[236:239]
	v_mfma_f32_16x16x32_bf16 v[240:243], v[52:55], v[4:7], v[240:243]
	s_cmp_lg_u32 s22, s21
	s_cbranch_scc0 .Lc2_nokpf
	v_lshl_add_u64 v[120:121], v[120:121], 0, s[0:1]
	v_lshl_add_u64 v[122:123], v[122:123], 0, s[0:1]
	global_load_dwordx4 v[24:27], v[120:121], off offset:-4096
	global_load_dwordx4 v[28:31], v[120:121], off offset:-3072
	global_load_dwordx4 v[32:35], v[120:121], off offset:-2048
	global_load_dwordx4 v[36:39], v[120:121], off offset:-1024
	global_load_dwordx4 v[40:43], v[120:121], off offset:0
	global_load_dwordx4 v[44:47], v[120:121], off offset:1024
	global_load_dwordx4 v[48:51], v[120:121], off offset:2048
	global_load_dwordx4 v[52:55], v[120:121], off offset:3072
.Lc2_nokpf:
	s_waitcnt lgkmcnt(0)
	s_nop 7
	s_cmp_lg_u32 s26, 0
	s_cbranch_scc0 .Lc2_gadd
	v_add_f32_e32 v244, v228, v125
	v_add_f32_e32 v245, v229, v125
	v_add_f32_e32 v246, v230, v125
	v_add_f32_e32 v247, v231, v125
	v_add_f32_e32 v248, v232, v125
	v_add_f32_e32 v249, v233, v125
	v_add_f32_e32 v250, v234, v125
	v_add_f32_e32 v251, v235, v125
	v_add_f32_e32 v252, v236, v125
	v_add_f32_e32 v253, v237, v125
	v_add_f32_e32 v255, v238, v125
	v_add_f32_e32 v98, v239, v125
	v_add_f32_e32 v99, v240, v125
	v_add_f32_e32 v116, v241, v125
	v_add_f32_e32 v117, v242, v125
	v_add_f32_e32 v118, v243, v125
	s_branch .Lc2_added
.Lc2_gadd:
	v_add_f32_e32 v244, v228, v244
	v_add_f32_e32 v245, v229, v245
	v_add_f32_e32 v246, v230, v246
	v_add_f32_e32 v247, v231, v247
	v_add_f32_e32 v248, v232, v248
	v_add_f32_e32 v249, v233, v249
	v_add_f32_e32 v250, v234, v250
	v_add_f32_e32 v251, v235, v251
	v_add_f32_e32 v252, v236, v252
	v_add_f32_e32 v253, v237, v253
	v_add_f32_e32 v255, v238, v255
	v_add_f32_e32 v98, v239, v98
	v_add_f32_e32 v99, v240, v99
	v_add_f32_e32 v116, v241, v116
	v_add_f32_e32 v117, v242, v117
	v_add_f32_e32 v118, v243, v118
; #define LAS __attribute__((address_space(3)))
; __device__ __forceinline__ unsigned pk2(float lo, float hi) { return pg8::cvt_pk_bf16(lo, hi); }
; __device__ __forceinline__ float fexp(float x) { return __expf(x); }
; __device__ __forceinline__ void nsa_wave(CArgs* Ap, int l, int b, int g, int tq0, const LAS float* lut, LAS float* imp, int lane) {
;     ...
;                     const float lg = acc[nt][i] + lutg[dc * 4];
;                     float p = (dist >= 0) ? fexp(lg - mfin) * inv : 0.f;
;                     acc[nt][i] = p;
;                     p += __shfl_xor(p, 1); p += __shfl_xor(p, 2);
;                     pi4[i] = p;
;                 }
;                 if (r == 0) *(LAS f32x4*)(imp + qi * 512 + cb * 64 + 16 * nt + 4 * g4) = pi4;
;             }
; #pragma unroll
;             for (int hh = 0; hh < 2; ++hh) { u32x4 w; w.x = pk2(acc[2 * hh][0], acc[2 * hh][1]); w.y = pk2(acc[2 * hh][2], acc[2 * hh][3]); w.z = pk2(acc[2 * hh + 1][0], acc[2 * hh + 1][1]); w.w = pk2(acc[2 * hh + 1][2], acc[2 * hh + 1][3]);
;                 pB[hh] = __builtin_bit_cast(bf16x8, w); }
;             pv_acc(outacc, vf, pB);
.Lc2_added:
	v_fmamk_f32 v244, v244, 0x3fb8aa3b, v126
	v_fmamk_f32 v245, v245, 0x3fb8aa3b, v126
	v_fmamk_f32 v246, v246, 0x3fb8aa3b, v126
	v_fmamk_f32 v247, v247, 0x3fb8aa3b, v126
	v_fmamk_f32 v248, v248, 0x3fb8aa3b, v126
	v_fmamk_f32 v249, v249, 0x3fb8aa3b, v126
	v_fmamk_f32 v250, v250, 0x3fb8aa3b, v126
	v_fmamk_f32 v251, v251, 0x3fb8aa3b, v126
	v_fmamk_f32 v252, v252, 0x3fb8aa3b, v126
	v_fmamk_f32 v253, v253, 0x3fb8aa3b, v126
	v_fmamk_f32 v255, v255, 0x3fb8aa3b, v126
	v_fmamk_f32 v98, v98, 0x3fb8aa3b, v126
	v_fmamk_f32 v99, v99, 0x3fb8aa3b, v126
	v_fmamk_f32 v116, v116, 0x3fb8aa3b, v126
	v_fmamk_f32 v117, v117, 0x3fb8aa3b, v126
	v_fmamk_f32 v118, v118, 0x3fb8aa3b, v126
	v_exp_f32_e32 v244, v244
	v_exp_f32_e32 v245, v245
	v_exp_f32_e32 v246, v246
	v_exp_f32_e32 v247, v247
	v_exp_f32_e32 v248, v248
	v_exp_f32_e32 v249, v249
	v_exp_f32_e32 v250, v250
	v_exp_f32_e32 v251, v251
	v_exp_f32_e32 v252, v252
	v_exp_f32_e32 v253, v253
	v_exp_f32_e32 v255, v255
	v_exp_f32_e32 v98, v98
	v_exp_f32_e32 v99, v99
	v_exp_f32_e32 v116, v116
	v_exp_f32_e32 v117, v117
	v_exp_f32_e32 v118, v118
	v_mul_f32_e32 v244, v80, v244
	v_mul_f32_e32 v245, v80, v245
	v_mul_f32_e32 v246, v80, v246
	v_mul_f32_e32 v247, v80, v247
	v_mul_f32_e32 v248, v80, v248
	v_mul_f32_e32 v249, v80, v249
	v_mul_f32_e32 v250, v80, v250
	v_mul_f32_e32 v251, v80, v251
	v_mul_f32_e32 v252, v80, v252
	v_mul_f32_e32 v253, v80, v253
	v_mul_f32_e32 v255, v80, v255
	v_mul_f32_e32 v98, v80, v98
	v_mul_f32_e32 v99, v80, v99
	v_mul_f32_e32 v116, v80, v116
	v_mul_f32_e32 v117, v80, v117
	v_mul_f32_e32 v118, v80, v118
	s_cmp_lg_u32 s26, 0
	s_cbranch_scc1 .Lc2_nomask
	v_cndmask_b32_e64 v244, 0, v244, s[46:47]
	v_cndmask_b32_e64 v245, 0, v245, s[48:49]
	v_cndmask_b32_e64 v246, 0, v246, s[50:51]
	v_cndmask_b32_e64 v247, 0, v247, s[52:53]
	v_cndmask_b32_e64 v248, 0, v248, s[54:55]
	v_cndmask_b32_e64 v249, 0, v249, s[56:57]
	v_cndmask_b32_e64 v250, 0, v250, s[58:59]
	v_cndmask_b32_e64 v251, 0, v251, s[60:61]
	v_cndmask_b32_e64 v252, 0, v252, s[62:63]
	v_cndmask_b32_e64 v253, 0, v253, s[64:65]
	v_cndmask_b32_e64 v255, 0, v255, s[66:67]
	v_cndmask_b32_e64 v98, 0, v98, s[68:69]
	v_cndmask_b32_e64 v99, 0, v99, s[96:97]
	v_cndmask_b32_e64 v116, 0, v116, s[98:99]
	v_cndmask_b32_e64 v117, 0, v117, s[100:101]
	v_cndmask_b32_e64 v118, 0, v118, s[76:77]
.Lc2_nomask:
	v_add_f32_dpp v228, v244, v244 quad_perm:[1,0,3,2] row_mask:0xf bank_mask:0xf
	v_add_f32_dpp v229, v245, v245 quad_perm:[1,0,3,2] row_mask:0xf bank_mask:0xf
	v_add_f32_dpp v230, v246, v246 quad_perm:[1,0,3,2] row_mask:0xf bank_mask:0xf
	v_add_f32_dpp v231, v247, v247 quad_perm:[1,0,3,2] row_mask:0xf bank_mask:0xf
	v_add_f32_dpp v232, v248, v248 quad_perm:[1,0,3,2] row_mask:0xf bank_mask:0xf
	v_add_f32_dpp v233, v249, v249 quad_perm:[1,0,3,2] row_mask:0xf bank_mask:0xf
	v_add_f32_dpp v234, v250, v250 quad_perm:[1,0,3,2] row_mask:0xf bank_mask:0xf
	v_add_f32_dpp v235, v251, v251 quad_perm:[1,0,3,2] row_mask:0xf bank_mask:0xf
	v_add_f32_dpp v236, v252, v252 quad_perm:[1,0,3,2] row_mask:0xf bank_mask:0xf
	v_add_f32_dpp v237, v253, v253 quad_perm:[1,0,3,2] row_mask:0xf bank_mask:0xf
	v_add_f32_dpp v238, v255, v255 quad_perm:[1,0,3,2] row_mask:0xf bank_mask:0xf
	v_add_f32_dpp v239, v98, v98 quad_perm:[1,0,3,2] row_mask:0xf bank_mask:0xf
	v_add_f32_dpp v240, v99, v99 quad_perm:[1,0,3,2] row_mask:0xf bank_mask:0xf
	v_add_f32_dpp v241, v116, v116 quad_perm:[1,0,3,2] row_mask:0xf bank_mask:0xf
	v_add_f32_dpp v242, v117, v117 quad_perm:[1,0,3,2] row_mask:0xf bank_mask:0xf
	v_add_f32_dpp v243, v118, v118 quad_perm:[1,0,3,2] row_mask:0xf bank_mask:0xf
	v_add_f32_dpp v228, v228, v228 quad_perm:[2,3,0,1] row_mask:0xf bank_mask:0xf
	v_add_f32_dpp v229, v229, v229 quad_perm:[2,3,0,1] row_mask:0xf bank_mask:0xf
	v_add_f32_dpp v230, v230, v230 quad_perm:[2,3,0,1] row_mask:0xf bank_mask:0xf
	v_add_f32_dpp v231, v231, v231 quad_perm:[2,3,0,1] row_mask:0xf bank_mask:0xf
	v_add_f32_dpp v232, v232, v232 quad_perm:[2,3,0,1] row_mask:0xf bank_mask:0xf
	v_add_f32_dpp v233, v233, v233 quad_perm:[2,3,0,1] row_mask:0xf bank_mask:0xf
	v_add_f32_dpp v234, v234, v234 quad_perm:[2,3,0,1] row_mask:0xf bank_mask:0xf
	v_add_f32_dpp v235, v235, v235 quad_perm:[2,3,0,1] row_mask:0xf bank_mask:0xf
	v_add_f32_dpp v236, v236, v236 quad_perm:[2,3,0,1] row_mask:0xf bank_mask:0xf
	v_add_f32_dpp v237, v237, v237 quad_perm:[2,3,0,1] row_mask:0xf bank_mask:0xf
	v_add_f32_dpp v238, v238, v238 quad_perm:[2,3,0,1] row_mask:0xf bank_mask:0xf
	v_add_f32_dpp v239, v239, v239 quad_perm:[2,3,0,1] row_mask:0xf bank_mask:0xf
	v_add_f32_dpp v240, v240, v240 quad_perm:[2,3,0,1] row_mask:0xf bank_mask:0xf
	v_add_f32_dpp v241, v241, v241 quad_perm:[2,3,0,1] row_mask:0xf bank_mask:0xf
	v_add_f32_dpp v242, v242, v242 quad_perm:[2,3,0,1] row_mask:0xf bank_mask:0xf
	v_add_f32_dpp v243, v243, v243 quad_perm:[2,3,0,1] row_mask:0xf bank_mask:0xf
	s_mov_b64 exec, s[2:3]
	ds_write_b128 v124, v[228:231]
	ds_write_b128 v124, v[232:235] offset:64
	ds_write_b128 v124, v[236:239] offset:128
	ds_write_b128 v124, v[240:243] offset:192
	s_mov_b64 exec, -1
	v_add_u32_e32 v124, 0x100, v124
	v_cvt_pk_bf16_f32 v244, v244, v245
	v_cvt_pk_bf16_f32 v245, v246, v247
	v_cvt_pk_bf16_f32 v246, v248, v249
	v_cvt_pk_bf16_f32 v247, v250, v251
	v_cvt_pk_bf16_f32 v248, v252, v253
	v_cvt_pk_bf16_f32 v249, v255, v98
	v_cvt_pk_bf16_f32 v250, v99, v116
	v_cvt_pk_bf16_f32 v251, v117, v118
	s_cmp_lg_u32 s22, s21
	s_cbranch_scc0 .Lc2_last
	s_waitcnt vmcnt(8)
	v_mfma_f32_16x16x32_bf16 v[16:19], v[56:59], v[244:247], v[16:19]
	v_mfma_f32_16x16x32_bf16 v[20:23], v[64:67], v[244:247], v[20:23]
	v_mfma_f32_16x16x32_bf16 v[12:15], v[100:103], v[244:247], v[12:15]
	v_mfma_f32_16x16x32_bf16 v[8:11], v[108:111], v[244:247], v[8:11]
	v_mfma_f32_16x16x32_bf16 v[16:19], v[60:63], v[248:251], v[16:19]
	v_mfma_f32_16x16x32_bf16 v[20:23], v[68:71], v[248:251], v[20:23]
	v_mfma_f32_16x16x32_bf16 v[12:15], v[104:107], v[248:251], v[12:15]
	v_mfma_f32_16x16x32_bf16 v[8:11], v[112:115], v[248:251], v[8:11]
	global_load_dwordx4 v[56:59], v[122:123], off offset:-4096
	global_load_dwordx4 v[60:63], v[122:123], off offset:-3072
	global_load_dwordx4 v[64:67], v[122:123], off offset:-2048
	global_load_dwordx4 v[68:71], v[122:123], off offset:-1024
	global_load_dwordx4 v[100:103], v[122:123], off offset:0
	global_load_dwordx4 v[104:107], v[122:123], off offset:1024
	global_load_dwordx4 v[108:111], v[122:123], off offset:2048
	global_load_dwordx4 v[112:115], v[122:123], off offset:3072
	s_branch .Lc2_loop
